# min3 + ATTN tile loop as staggered two-half ping-pong: LOAD segment (all LDS reads) | barrier | COMPUTE segment (all MFMAs + exp/pack), halves one barrier apart
# speedup vs baseline: 1.0097x; 1.0097x over previous
.LBB0_946:
	s_cmp_lt_u32 s93, 4
	s_cbranch_scc0 .Lpp_post
	s_barrier

.LBB0_952:
	s_lshl_b32 s6, s5, 8
	s_add_i32 s14, s6, s16
	s_add_u32 s12, s8, s14
	s_addc_u32 s13, s9, 0
	s_lshl_b64 s[6:7], s[12:13], 10
	v_lshl_add_u64 v[4:5], v[114:115], 0, s[6:7]
	s_mov_b32 s15, s11
	global_load_dwordx4 v[98:101], v[4:5], off offset:32
	global_load_dwordx4 v[102:105], v[4:5], off offset:64
	global_load_dwordx4 v[106:109], v[4:5], off offset:96
	v_lshl_add_u64 v[136:137], s[14:15], 3, v[120:121]
	global_load_dwordx4 v[110:113], v[4:5], off
	global_load_dwordx2 v[138:139], v[136:137], off
	s_waitcnt lgkmcnt(0)
	s_barrier
	s_mov_b32 m0, s21
	global_load_lds_dwordx4 v[116:117], off
	s_mov_b32 m0, s22
	global_load_lds_dwordx4 v[118:119], off
	v_mov_b32_e32 v16, v2
	s_mov_b32 m0, s23
	global_load_lds_dwordx4 v[122:123], off
	s_mov_b32 m0, s24
	global_load_lds_dwordx4 v[124:125], off
	s_waitcnt vmcnt(2)
	v_mov_b32_e32 v17, v2
	s_lshl_b32 s6, s5, 2
	s_lshl_b32 s30, s5, 10
	v_mov_b32_e32 v3, v2
	v_mov_b32_e32 v4, v2
	v_mov_b32_e32 v5, v2
	v_mov_b32_e32 v6, v2
	v_mov_b32_e32 v7, v2
	v_mov_b32_e32 v8, v2
	v_mov_b32_e32 v9, v2
	v_mov_b32_e32 v10, v2
	v_mov_b32_e32 v11, v2
	v_mov_b32_e32 v12, v2
	v_mov_b32_e32 v13, v2
	v_mov_b32_e32 v14, v2
	v_mov_b32_e32 v15, v2
	v_mov_b64_e32 v[48:49], v[16:17]
	v_mov_b64_e32 v[32:33], v[16:17]
	v_mov_b64_e32 v[64:65], v[16:17]
	s_mov_b32 s15, 2
	s_add_i32 s27, s6, 4
	s_lshr_b32 s28, s14, 6
	s_or_b32 s29, s6, 3
	v_add_u32_e32 v148, s30, v142
	s_addk_i32 s30, 0x400
	s_mov_b32 s31, 0
	s_movk_i32 s33, 0xaf
	v_mov_b64_e32 v[46:47], v[14:15]
	v_mov_b64_e32 v[44:45], v[12:13]
	v_mov_b64_e32 v[42:43], v[10:11]
	v_mov_b64_e32 v[40:41], v[8:9]
	v_mov_b64_e32 v[38:39], v[6:7]
	v_mov_b64_e32 v[36:37], v[4:5]
	v_mov_b64_e32 v[34:35], v[2:3]
	v_mov_b64_e32 v[30:31], v[14:15]
	v_mov_b64_e32 v[28:29], v[12:13]
	v_mov_b64_e32 v[26:27], v[10:11]
	v_mov_b64_e32 v[24:25], v[8:9]
	v_mov_b64_e32 v[22:23], v[6:7]
	v_mov_b64_e32 v[20:21], v[4:5]
	v_mov_b64_e32 v[18:19], v[2:3]
	v_mov_b64_e32 v[62:63], v[14:15]
	v_mov_b64_e32 v[60:61], v[12:13]
	v_mov_b64_e32 v[58:59], v[10:11]
	v_mov_b64_e32 v[56:57], v[8:9]
	v_mov_b64_e32 v[54:55], v[6:7]
	v_mov_b64_e32 v[52:53], v[4:5]
	v_mov_b64_e32 v[50:51], v[2:3]
	s_mov_b32 s34, 0
	s_cmp_lt_u32 s93, 4
	s_cbranch_scc1 .Lpp_pre
	s_barrier
.Lpp_pre:
	s_branch .LBB0_955
.LBB0_954:
	s_add_i32 s5, s34, 1
	s_cmp_lg_u32 s34, 2
	s_cselect_b32 s34, s5, 0
	s_addk_i32 s31, 0xff00
	s_waitcnt vmcnt(3)
	s_add_i32 s15, s15, 1
	s_add_i32 s5, s30, s31
	s_add_i32 s33, s33, 64
	s_cmp_eq_u32 s5, 0
	s_cbranch_scc1 .LBB0_946
.LBB0_955:
	s_add_i32 s35, s15, -2
	s_lshl_b32 s5, s34, 13
	s_cmp_lt_u32 s15, s27
	s_cselect_b32 s10, s15, s29
	s_lshl_b64 s[6:7], s[10:11], 16
	s_waitcnt vmcnt(0)
	v_lshrrev_b32_e32 v3, v1, v138
	v_lshl_add_u64 v[6:7], v[116:117], 0, s[6:7]
	v_lshl_add_u64 v[8:9], v[118:119], 0, s[6:7]
	s_add_i32 s6, s5, 0xffffe000
	v_lshlrev_b32_e32 v3, 4, v3
	s_cmp_lg_u32 s34, 0
	v_and_b32_e32 v4, 0xf0f0f0f0, v3
	v_lshrrev_b32_e32 v3, v1, v139
	s_cselect_b32 s6, s6, 0x4000
	v_lshlrev_b32_e32 v3, 4, v3
	s_add_i32 s6, s6, 0
	v_and_b32_e32 v3, 0xf0f0f0f0, v3
	s_add_i32 s6, s20, s6
	s_waitcnt lgkmcnt(0)
	s_barrier
	s_add_i32 s7, s6, 0x6000
	s_mov_b32 m0, s6
	global_load_lds_dwordx4 v[6:7], off
	s_mov_b32 m0, s7
	global_load_lds_dwordx4 v[8:9], off
	s_add_i32 s6, s15, -1
	s_cmp_lt_u32 s35, 63
	s_cselect_b32 s10, s6, 63
	s_lshl_b64 s[6:7], s[10:11], 15
	v_lshl_add_u64 v[6:7], v[136:137], 0, s[6:7]
	global_load_dwordx2 v[138:139], v[6:7], off
	s_cmp_gt_u32 s35, s28
	s_cbranch_scc1 .Lpp_skip
	v_add_u32_e32 v149, s5, v140
	v_add_u32_e32 v150, s5, v141
	v_add_u32_sdwa v230, v4, s25 dst_sel:DWORD dst_unused:UNUSED_PAD src0_sel:BYTE_0 src1_sel:DWORD
	v_add_u32_sdwa v231, v4, s25 dst_sel:DWORD dst_unused:UNUSED_PAD src0_sel:BYTE_1 src1_sel:DWORD
	v_add_u32_sdwa v232, v4, s25 dst_sel:DWORD dst_unused:UNUSED_PAD src0_sel:BYTE_2 src1_sel:DWORD
	v_add_u32_sdwa v233, v4, s25 dst_sel:DWORD dst_unused:UNUSED_PAD src0_sel:BYTE_3 src1_sel:DWORD
	v_add_u32_sdwa v234, v3, s25 dst_sel:DWORD dst_unused:UNUSED_PAD src0_sel:BYTE_0 src1_sel:DWORD
	v_add_u32_sdwa v235, v3, s25 dst_sel:DWORD dst_unused:UNUSED_PAD src0_sel:BYTE_1 src1_sel:DWORD
	v_add_u32_sdwa v236, v3, s25 dst_sel:DWORD dst_unused:UNUSED_PAD src0_sel:BYTE_2 src1_sel:DWORD
	v_add_u32_sdwa v237, v3, s25 dst_sel:DWORD dst_unused:UNUSED_PAD src0_sel:BYTE_3 src1_sel:DWORD
	ds_read_b128 v[66:69], v230
	ds_read_b128 v[70:73], v231
	ds_read_b128 v[74:77], v232
	ds_read_b128 v[78:81], v233
	ds_read_b128 v[182:185], v149
	ds_read_b128 v[186:189], v149 offset:2048
	ds_read_b128 v[190:193], v149 offset:4096
	ds_read_b128 v[194:197], v149 offset:6144
	ds_read_b128 v[82:85], v234
	ds_read_b128 v[86:89], v235
	ds_read_b128 v[90:93], v236
	ds_read_b128 v[94:97], v237
	s_waitcnt lgkmcnt(8)
	ds_read_b128 v[198:201], v149 offset:512
	ds_read_b128 v[202:205], v149 offset:2560
	ds_read_b128 v[206:209], v149 offset:4608
	ds_read_b128 v[210:213], v149 offset:6656
	s_waitcnt lgkmcnt(8)
	ds_read_b64_tr_b16 v[152:153], v150
	ds_read_b64_tr_b16 v[154:155], v150 offset:512
	ds_read_b64_tr_b16 v[156:157], v150 offset:1024
	ds_read_b64_tr_b16 v[158:159], v150 offset:1536
	s_waitcnt lgkmcnt(8)
	ds_read_b64_tr_b16 v[160:161], v150 offset:2048
	ds_read_b64_tr_b16 v[162:163], v150 offset:2560
	ds_read_b64_tr_b16 v[164:165], v150 offset:3072
	ds_read_b64_tr_b16 v[166:167], v150 offset:3584
	s_waitcnt lgkmcnt(8)
	ds_read_b64_tr_b16 v[168:169], v150 offset:4096
	ds_read_b64_tr_b16 v[170:171], v150 offset:4608
	ds_read_b64_tr_b16 v[172:173], v150 offset:5120
	ds_read_b64_tr_b16 v[174:175], v150 offset:5632
	s_waitcnt lgkmcnt(8)
	ds_read_b64_tr_b16 v[214:215], v150 offset:6144
	ds_read_b64_tr_b16 v[216:217], v150 offset:6656
	ds_read_b64_tr_b16 v[218:219], v150 offset:7168
	ds_read_b64_tr_b16 v[220:221], v150 offset:7680
	s_waitcnt lgkmcnt(0)
	s_barrier
	v_mfma_f32_32x32x16_bf16 v[66:81], v[182:185], v[110:113], v[66:81]
	v_mfma_f32_32x32x16_bf16 v[66:81], v[186:189], v[98:101], v[66:81]
	v_mfma_f32_32x32x16_bf16 v[66:81], v[190:193], v[102:105], v[66:81]
	v_mfma_f32_32x32x16_bf16 v[66:81], v[194:197], v[106:109], v[66:81]
	s_cmp_lt_u32 s33, s14
	s_cbranch_scc0 .Lpp_bias
	v_mfma_f32_32x32x16_bf16 v[82:97], v[198:201], v[110:113], v[82:97]
	v_mfma_f32_32x32x16_bf16 v[82:97], v[202:205], v[98:101], v[82:97]
	s_nop 7
	s_nop 1
	v_exp_f32_e32 v66, v66
	v_exp_f32_e32 v67, v67
	v_exp_f32_e32 v68, v68
	v_exp_f32_e32 v69, v69
	v_mfma_f32_32x32x16_bf16 v[82:97], v[206:209], v[102:105], v[82:97]
	v_exp_f32_e32 v70, v70
	v_exp_f32_e32 v71, v71
	v_exp_f32_e32 v72, v72
	v_exp_f32_e32 v73, v73
	v_mfma_f32_32x32x16_bf16 v[82:97], v[210:213], v[106:109], v[82:97]
	v_exp_f32_e32 v74, v74
	v_exp_f32_e32 v75, v75
	v_exp_f32_e32 v76, v76
	v_exp_f32_e32 v77, v77
	v_exp_f32_e32 v78, v78
	v_exp_f32_e32 v79, v79
	v_exp_f32_e32 v80, v80
	v_exp_f32_e32 v81, v81
	v_cvt_pk_bf16_f32 v4, v66, v67
	v_cvt_pk_bf16_f32 v5, v68, v69
	v_cvt_pk_bf16_f32 v6, v70, v71
	v_cvt_pk_bf16_f32 v7, v72, v73
	v_cvt_pk_bf16_f32 v8, v74, v75
	v_cvt_pk_bf16_f32 v9, v76, v77
	v_cvt_pk_bf16_f32 v10, v78, v79
	v_cvt_pk_bf16_f32 v11, v80, v81
	v_mfma_f32_32x32x16_bf16 v[34:49], v[4:7], v[152:155], v[34:49]
	v_exp_f32_e32 v82, v82
	v_exp_f32_e32 v83, v83
	v_exp_f32_e32 v84, v84
	v_mfma_f32_32x32x16_bf16 v[18:33], v[4:7], v[168:171], v[18:33]
	v_exp_f32_e32 v85, v85
	v_exp_f32_e32 v86, v86
	v_exp_f32_e32 v87, v87
	v_mfma_f32_32x32x16_bf16 v[50:65], v[4:7], v[226:229], v[50:65]
	v_exp_f32_e32 v88, v88
	v_exp_f32_e32 v89, v89
	v_exp_f32_e32 v90, v90
	v_mfma_f32_32x32x16_bf16 v[34:49], v[8:11], v[156:159], v[34:49]
	v_exp_f32_e32 v91, v91
	v_exp_f32_e32 v92, v92
	v_exp_f32_e32 v93, v93
	v_mfma_f32_32x32x16_bf16 v[18:33], v[8:11], v[172:175], v[18:33]
	v_exp_f32_e32 v94, v94
	v_exp_f32_e32 v95, v95
	v_exp_f32_e32 v96, v96
	v_exp_f32_e32 v97, v97
	v_mfma_f32_32x32x16_bf16 v[50:65], v[8:11], v[226:229], v[50:65]
	v_cvt_pk_bf16_f32 v12, v82, v83
	v_cvt_pk_bf16_f32 v13, v84, v85
	v_cvt_pk_bf16_f32 v14, v86, v87
	v_cvt_pk_bf16_f32 v15, v88, v89
	v_cvt_pk_bf16_f32 v222, v90, v91
	v_cvt_pk_bf16_f32 v223, v92, v93
	v_cvt_pk_bf16_f32 v224, v94, v95
	v_cvt_pk_bf16_f32 v225, v96, v97
	s_nop 1
	v_mfma_f32_32x32x16_bf16 v[34:49], v[12:15], v[160:163], v[34:49]
	v_mfma_f32_32x32x16_bf16 v[18:33], v[12:15], v[214:217], v[18:33]
	v_mfma_f32_32x32x16_bf16 v[50:65], v[12:15], v[226:229], v[50:65]
	v_mfma_f32_32x32x16_bf16 v[34:49], v[222:225], v[164:167], v[34:49]
	v_mfma_f32_32x32x16_bf16 v[18:33], v[222:225], v[218:221], v[18:33]
	v_mfma_f32_32x32x16_bf16 v[50:65], v[222:225], v[226:229], v[50:65]
	s_branch .LBB0_954
.Lpp_bias:
	v_mfma_f32_32x32x16_bf16 v[82:97], v[198:201], v[110:113], v[82:97]
	v_mfma_f32_32x32x16_bf16 v[82:97], v[202:205], v[98:101], v[82:97]
	v_mfma_f32_32x32x16_bf16 v[82:97], v[206:209], v[102:105], v[82:97]
	v_mfma_f32_32x32x16_bf16 v[82:97], v[210:213], v[106:109], v[82:97]
	v_add_u32_e32 v3, s31, v148
	v_add_u32_e32 v4, 0x149fc, v3
	v_add_u32_e32 v6, 0x1497c, v3
	v_add_u32_e32 v8, 0x149f4, v3
	ds_read2_b32 v[4:5], v4 offset1:1
	ds_read2_b32 v[6:7], v6 offset1:1
	ds_read2_b32 v[8:9], v8 offset1:1
	v_add_u32_e32 v10, 0x14974, v3
	v_add_u32_e32 v12, 0x14954, v3
	s_waitcnt lgkmcnt(2)
	v_pk_add_f32 v[66:67], v[66:67], v[4:5] op_sel:[0,1] op_sel_hi:[1,0]
	s_waitcnt lgkmcnt(1)
	v_pk_add_f32 v[82:83], v[82:83], v[6:7] op_sel:[0,1] op_sel_hi:[1,0]
	s_waitcnt lgkmcnt(0)
	v_pk_add_f32 v[68:69], v[68:69], v[8:9] op_sel:[0,1] op_sel_hi:[1,0]
	v_add_u32_e32 v4, 0x149dc, v3
	v_add_u32_e32 v6, 0x1495c, v3
	v_add_u32_e32 v8, 0x149d4, v3
	ds_read2_b32 v[10:11], v10 offset1:1
	ds_read2_b32 v[4:5], v4 offset1:1
	ds_read2_b32 v[6:7], v6 offset1:1
	ds_read2_b32 v[8:9], v8 offset1:1
	ds_read2_b32 v[12:13], v12 offset1:1
	s_waitcnt lgkmcnt(3)
	v_pk_add_f32 v[70:71], v[70:71], v[4:5] op_sel:[0,1] op_sel_hi:[1,0]
	s_waitcnt lgkmcnt(2)
	v_pk_add_f32 v[86:87], v[86:87], v[6:7] op_sel:[0,1] op_sel_hi:[1,0]
	s_waitcnt lgkmcnt(1)
	v_pk_add_f32 v[72:73], v[72:73], v[8:9] op_sel:[0,1] op_sel_hi:[1,0]
	v_add_u32_e32 v4, 0x149bc, v3
	v_add_u32_e32 v6, 0x1493c, v3
	v_add_u32_e32 v8, 0x149b4, v3
	ds_read2_b32 v[4:5], v4 offset1:1
	ds_read2_b32 v[6:7], v6 offset1:1
	ds_read2_b32 v[8:9], v8 offset1:1
	v_pk_add_f32 v[84:85], v[84:85], v[10:11] op_sel:[0,1] op_sel_hi:[1,0]
	v_add_u32_e32 v10, 0x14934, v3
	s_waitcnt lgkmcnt(2)
	v_pk_add_f32 v[74:75], v[74:75], v[4:5] op_sel:[0,1] op_sel_hi:[1,0]
	s_waitcnt lgkmcnt(1)
	v_pk_add_f32 v[90:91], v[90:91], v[6:7] op_sel:[0,1] op_sel_hi:[1,0]
	s_waitcnt lgkmcnt(0)
	v_pk_add_f32 v[76:77], v[76:77], v[8:9] op_sel:[0,1] op_sel_hi:[1,0]
	v_add_u32_e32 v4, 0x1499c, v3
	v_add_u32_e32 v6, 0x1491c, v3
	v_add_u32_e32 v8, 0x14994, v3
	v_pk_add_f32 v[88:89], v[88:89], v[12:13] op_sel:[0,1] op_sel_hi:[1,0]
	ds_read2_b32 v[10:11], v10 offset1:1
	v_add_u32_e32 v3, 0x14914, v3
	ds_read2_b32 v[4:5], v4 offset1:1
	ds_read2_b32 v[6:7], v6 offset1:1
	ds_read2_b32 v[8:9], v8 offset1:1
	ds_read2_b32 v[12:13], v3 offset1:1
	s_waitcnt lgkmcnt(3)
	v_pk_add_f32 v[78:79], v[78:79], v[4:5] op_sel:[0,1] op_sel_hi:[1,0]
	v_pk_add_f32 v[92:93], v[92:93], v[10:11] op_sel:[0,1] op_sel_hi:[1,0]
	s_waitcnt lgkmcnt(2)
	v_pk_add_f32 v[94:95], v[94:95], v[6:7] op_sel:[0,1] op_sel_hi:[1,0]
	s_waitcnt lgkmcnt(1)
	v_pk_add_f32 v[80:81], v[80:81], v[8:9] op_sel:[0,1] op_sel_hi:[1,0]
	s_waitcnt lgkmcnt(0)
	v_pk_add_f32 v[96:97], v[96:97], v[12:13] op_sel:[0,1] op_sel_hi:[1,0]
	v_exp_f32_e32 v66, v66
	v_exp_f32_e32 v67, v67
	v_exp_f32_e32 v68, v68
	v_exp_f32_e32 v69, v69
	v_exp_f32_e32 v70, v70
	v_exp_f32_e32 v71, v71
	v_exp_f32_e32 v72, v72
	v_exp_f32_e32 v73, v73
	v_exp_f32_e32 v74, v74
	v_exp_f32_e32 v75, v75
	v_exp_f32_e32 v76, v76
	v_exp_f32_e32 v77, v77
	v_exp_f32_e32 v78, v78
	v_exp_f32_e32 v79, v79
	v_exp_f32_e32 v80, v80
	v_exp_f32_e32 v81, v81
	v_cvt_pk_bf16_f32 v4, v66, v67
	v_cvt_pk_bf16_f32 v5, v68, v69
	v_cvt_pk_bf16_f32 v6, v70, v71
	v_cvt_pk_bf16_f32 v7, v72, v73
	v_cvt_pk_bf16_f32 v8, v74, v75
	v_cvt_pk_bf16_f32 v9, v76, v77
	v_cvt_pk_bf16_f32 v10, v78, v79
	v_cvt_pk_bf16_f32 v11, v80, v81
	v_mfma_f32_32x32x16_bf16 v[34:49], v[4:7], v[152:155], v[34:49]
	v_exp_f32_e32 v82, v82
	v_exp_f32_e32 v83, v83
	v_exp_f32_e32 v84, v84
	v_mfma_f32_32x32x16_bf16 v[18:33], v[4:7], v[168:171], v[18:33]
	v_exp_f32_e32 v85, v85
	v_exp_f32_e32 v86, v86
	v_exp_f32_e32 v87, v87
	v_mfma_f32_32x32x16_bf16 v[50:65], v[4:7], v[226:229], v[50:65]
	v_exp_f32_e32 v88, v88
	v_exp_f32_e32 v89, v89
	v_exp_f32_e32 v90, v90
	v_mfma_f32_32x32x16_bf16 v[34:49], v[8:11], v[156:159], v[34:49]
	v_exp_f32_e32 v91, v91
	v_exp_f32_e32 v92, v92
	v_exp_f32_e32 v93, v93
	v_mfma_f32_32x32x16_bf16 v[18:33], v[8:11], v[172:175], v[18:33]
	v_exp_f32_e32 v94, v94
	v_exp_f32_e32 v95, v95
	v_exp_f32_e32 v96, v96
	v_exp_f32_e32 v97, v97
	v_mfma_f32_32x32x16_bf16 v[50:65], v[8:11], v[226:229], v[50:65]
	v_cvt_pk_bf16_f32 v12, v82, v83
	v_cvt_pk_bf16_f32 v13, v84, v85
	v_cvt_pk_bf16_f32 v14, v86, v87
	v_cvt_pk_bf16_f32 v15, v88, v89
	v_cvt_pk_bf16_f32 v222, v90, v91
	v_cvt_pk_bf16_f32 v223, v92, v93
	v_cvt_pk_bf16_f32 v224, v94, v95
	v_cvt_pk_bf16_f32 v225, v96, v97
	s_nop 1
	v_mfma_f32_32x32x16_bf16 v[34:49], v[12:15], v[160:163], v[34:49]
	v_mfma_f32_32x32x16_bf16 v[18:33], v[12:15], v[214:217], v[18:33]
	v_mfma_f32_32x32x16_bf16 v[50:65], v[12:15], v[226:229], v[50:65]
	v_mfma_f32_32x32x16_bf16 v[34:49], v[222:225], v[164:167], v[34:49]
	v_mfma_f32_32x32x16_bf16 v[18:33], v[222:225], v[218:221], v[18:33]
	v_mfma_f32_32x32x16_bf16 v[50:65], v[222:225], v[226:229], v[50:65]
	s_branch .LBB0_954
.Lpp_skip:
	s_waitcnt lgkmcnt(0)
	s_barrier
	s_branch .LBB0_954
